# EpiResid epilogues (out-proj and FFN2 GEMMs): gate load hoisted, residual loads issued up front per half with counted vmcnt instead of one serialized round trip per row group
# speedup vs baseline: 1.0202x; 1.0202x over previous
;   DI void operator()(int m, int n, f32x4 v) const {
;     const int row = m + row0;
;     const float* s = row < TL ? sl + (size_t)row * DM : sc + (size_t)(row - TL) * DM;
;     float* d = row < TL ? dl + (size_t)row * DM : dc + (size_t)(row - TL) * DM;
;     const int mi = row < TL ? (row >> 14) : 2;
;     const f32x4 g = *(const f32x4*)(gate + mi * 6144 + n);
;     const f32x4 r = *(const f32x4*)(s + n);
;     f32x4 o;
; #pragma unroll
;     for (int j = 0; j < 4; ++j) o[j] = r[j] + g[j] * v[j];
;     *(f32x4*)(d + n) = o;
;   }
; template <class Epi>
; DI void gemm_phase512(const bf16_t* A, const bf16_t* Bt, int mtiles, int ntiles, int K, int Kper, int ksplit, const Epi& epi,
;                       unsigned char* smem, int bid, int nb) {
;     ...
;       } else {
; #pragma unroll
;         for (int half = 0; half < 2; ++half) {
;           if (half) asm volatile("" ::: "memory");
; #pragma unroll
;           for (int ni = 0; ni < 2; ++ni)
; #pragma unroll
;             for (int mh = 0; mh < 2; ++mh)
; #pragma unroll
;               for (int g = 0; g < 4; ++g) {
;                 const int mi = 2 * half + mh;
;                 f32x4 v = {acc[ni][mi][4 * g], acc[ni][mi][4 * g + 1], acc[ni][mi][4 * g + 2], acc[ni][mi][4 * g + 3]};
;                 *(f32x4*)(wl + (mh * 32 + l31) * 272 + (ni * 32 + 8 * g + 4 * hh) * 4) = v;
;               }
;           asm volatile("" ::: "memory");
; #pragma unroll
;           for (int i = 0; i < 16; ++i) {
;             const int row = (lane >> 4) + 4 * i, ch = lane & 15;
;             const f32x4 v = *(const f32x4*)(wl + row * 272 + ch * 16);
;             epi(m0 + half * 64 + row, n0 + ch * 4, v);
;           }
.LBB0_581:
	s_waitcnt vmcnt(5)
	v_add_co_u32_e32 v132, vcc, 0x20000, v166
	v_lshl_or_b32 v197, s29, 8, v171
	s_nop 0
	v_addc_co_u32_e32 v133, vcc, 0, v167, vcc
	s_waitcnt vmcnt(4)
	v_add_co_u32_e32 v136, vcc, 0x20000, v168
	global_load_dwordx4 v[128:131], v[166:167], off
	s_nop 0
	v_addc_co_u32_e32 v137, vcc, 0, v169, vcc
	s_waitcnt vmcnt(4)
	v_add_co_u32_e32 v140, vcc, 0x40000, v166
	global_load_dwordx4 v[132:135], v[132:133], off
	s_nop 0
	v_addc_co_u32_e32 v141, vcc, 0, v167, vcc
	s_waitcnt vmcnt(4)
	v_add_co_u32_e32 v144, vcc, 0x40000, v168
	global_load_dwordx4 v[136:139], v[136:137], off
	s_nop 0
	v_addc_co_u32_e32 v145, vcc, 0, v169, vcc
	v_add_co_u32_e32 v148, vcc, 0x60000, v166
	global_load_dwordx4 v[140:143], v[140:141], off
	s_nop 0
	v_addc_co_u32_e32 v149, vcc, 0, v167, vcc
	s_waitcnt vmcnt(5)
	v_add_co_u32_e32 v152, vcc, 0x60000, v168
	global_load_dwordx4 v[144:147], v[144:145], off
	s_nop 0
	v_addc_co_u32_e32 v153, vcc, 0, v169, vcc
	global_load_dwordx4 v[148:151], v[148:149], off
	s_nop 0
	global_load_dwordx4 v[156:159], v[168:169], off
	s_nop 0
	global_load_dwordx4 v[152:155], v[152:153], off
	ds_write_b128 v191, v[112:115]
	ds_write_b128 v191, v[116:119] offset:32
	ds_write_b128 v191, v[120:123] offset:64
	ds_write_b128 v191, v[124:127] offset:96
	ds_write_b128 v191, v[96:99] offset:8704
	ds_write_b128 v191, v[100:103] offset:8736
	ds_write_b128 v191, v[104:107] offset:8768
	ds_write_b128 v191, v[108:111] offset:8800
	ds_write_b128 v191, v[80:83] offset:128
	ds_write_b128 v191, v[84:87] offset:160
	ds_write_b128 v191, v[88:91] offset:192
	ds_write_b128 v191, v[92:95] offset:224
	ds_write_b128 v191, v[64:67] offset:8832
	ds_write_b128 v191, v[68:71] offset:8864
	ds_write_b128 v191, v[72:75] offset:8896
	ds_write_b128 v191, v[76:79] offset:8928
	v_lshl_add_u32 v198, s28, 8, v173
	v_ashrrev_i32_e32 v199, 31, v198
	v_or_b32_e32 v200, v197, v172
	v_lshlrev_b64 v[198:199], 2, v[198:199]
	v_readlane_b32 s30, v254, 50
	v_readlane_b32 s28, v254, 48
	v_readlane_b32 s31, v254, 51
	v_readlane_b32 s29, v254, 49
	v_cmp_gt_i32_e32 vcc, s34, v200
	v_add_u32_e32 v202, 0xffff8000, v200
	v_ashrrev_i32_e32 v203, 31, v200
	v_min_i32_e32 v204, 0x8000, v200
	v_cndmask_b32_e32 v203, 0, v203, vcc
	v_cndmask_b32_e32 v202, v202, v200, vcc
	v_ashrrev_i32_e32 v204, 14, v204
	v_lshlrev_b64 v[202:203], 12, v[202:203]
	v_mul_i32_i24_e32 v204, 0x1800, v204
	v_ashrrev_i32_e32 v205, 31, v204
	v_lshl_add_u64 v[206:207], v[204:205], 2, s[38:39]
	v_lshl_add_u64 v[206:207], v[206:207], 0, v[198:199]
	global_load_dwordx4 v[208:211], v[206:207], off
	v_mov_b32_e32 v239, s31
	v_mov_b32_e32 v201, s29
	v_mov_b32_e32 v238, s30
	v_mov_b32_e32 v200, s28
	v_cndmask_b32_e32 v239, v239, v201, vcc
	v_cndmask_b32_e32 v238, v238, v200, vcc
	v_mov_b32_e32 v241, s7
	v_mov_b32_e32 v201, s5
	v_mov_b32_e32 v240, s6
	v_mov_b32_e32 v200, s4
	v_cndmask_b32_e32 v241, v241, v201, vcc
	v_cndmask_b32_e32 v240, v240, v200, vcc
	v_lshl_add_u64 v[238:239], v[238:239], 0, v[202:203]
	v_lshl_add_u64 v[240:241], v[240:241], 0, v[202:203]
	v_lshl_add_u64 v[238:239], v[238:239], 0, v[198:199]
	v_lshl_add_u64 v[240:241], v[240:241], 0, v[198:199]
	s_mov_b32 s28, s27
	s_mov_b32 s29, s22
	s_mov_b32 s100, 0x4000
	s_mov_b32 s101, 0
	global_load_dwordx4 v[64:67], v[238:239], off
	v_lshl_add_u64 v[238:239], v[238:239], 0, s[100:101]
	global_load_dwordx4 v[68:71], v[238:239], off
	v_lshl_add_u64 v[238:239], v[238:239], 0, s[100:101]
	global_load_dwordx4 v[72:75], v[238:239], off
	v_lshl_add_u64 v[238:239], v[238:239], 0, s[100:101]
	global_load_dwordx4 v[76:79], v[238:239], off
	v_lshl_add_u64 v[238:239], v[238:239], 0, s[100:101]
	global_load_dwordx4 v[80:83], v[238:239], off
	v_lshl_add_u64 v[238:239], v[238:239], 0, s[100:101]
	global_load_dwordx4 v[84:87], v[238:239], off
	v_lshl_add_u64 v[238:239], v[238:239], 0, s[100:101]
	global_load_dwordx4 v[88:91], v[238:239], off
	v_lshl_add_u64 v[238:239], v[238:239], 0, s[100:101]
	global_load_dwordx4 v[92:95], v[238:239], off
	v_lshl_add_u64 v[238:239], v[238:239], 0, s[100:101]
	global_load_dwordx4 v[96:99], v[238:239], off
	v_lshl_add_u64 v[238:239], v[238:239], 0, s[100:101]
	global_load_dwordx4 v[100:103], v[238:239], off
	v_lshl_add_u64 v[238:239], v[238:239], 0, s[100:101]
	global_load_dwordx4 v[104:107], v[238:239], off
	v_lshl_add_u64 v[238:239], v[238:239], 0, s[100:101]
	global_load_dwordx4 v[108:111], v[238:239], off
	v_lshl_add_u64 v[238:239], v[238:239], 0, s[100:101]
	global_load_dwordx4 v[112:115], v[238:239], off
	v_lshl_add_u64 v[238:239], v[238:239], 0, s[100:101]
	global_load_dwordx4 v[116:119], v[238:239], off
	v_lshl_add_u64 v[238:239], v[238:239], 0, s[100:101]
	global_load_dwordx4 v[120:123], v[238:239], off
	v_lshl_add_u64 v[238:239], v[238:239], 0, s[100:101]
	global_load_dwordx4 v[124:127], v[238:239], off
	v_lshl_add_u64 v[238:239], v[238:239], 0, s[100:101]
	ds_read_b128 v[242:245], v192
	ds_read_b128 v[246:249], v192 offset:1088
	s_waitcnt vmcnt(15) lgkmcnt(1)
	v_pk_fma_f32 v[66:67], v[244:245], v[210:211], v[66:67]
	v_pk_fma_f32 v[64:65], v[242:243], v[208:209], v[64:65]
	global_store_dwordx4 v[240:241], v[64:67], off
	v_lshl_add_u64 v[240:241], v[240:241], 0, s[100:101]
	ds_read_b128 v[242:245], v192 offset:2176
	s_waitcnt vmcnt(15) lgkmcnt(1)
	v_pk_fma_f32 v[70:71], v[248:249], v[210:211], v[70:71]
	v_pk_fma_f32 v[68:69], v[246:247], v[208:209], v[68:69]
	global_store_dwordx4 v[240:241], v[68:71], off
	v_lshl_add_u64 v[240:241], v[240:241], 0, s[100:101]
	ds_read_b128 v[246:249], v192 offset:3264
	s_waitcnt vmcnt(15) lgkmcnt(1)
;   DI void operator()(int m, int n, f32x4 v) const {
;     const int row = m + row0;
;     const float* s = row < TL ? sl + (size_t)row * DM : sc + (size_t)(row - TL) * DM;
;     float* d = row < TL ? dl + (size_t)row * DM : dc + (size_t)(row - TL) * DM;
;     const int mi = row < TL ? (row >> 14) : 2;
;     const f32x4 g = *(const f32x4*)(gate + mi * 6144 + n);
;     const f32x4 r = *(const f32x4*)(s + n);
;     f32x4 o;
; #pragma unroll
;     for (int j = 0; j < 4; ++j) o[j] = r[j] + g[j] * v[j];
;     *(f32x4*)(d + n) = o;
;   }
; template <class Epi>
; DI void gemm_phase512(const bf16_t* A, const bf16_t* Bt, int mtiles, int ntiles, int K, int Kper, int ksplit, const Epi& epi,
;                       unsigned char* smem, int bid, int nb) {
;     ...
;         for (int half = 0; half < 2; ++half) {
;           if (half) asm volatile("" ::: "memory");
; #pragma unroll
;           for (int ni = 0; ni < 2; ++ni)
; #pragma unroll
;             for (int mh = 0; mh < 2; ++mh)
; #pragma unroll
;               for (int g = 0; g < 4; ++g) {
;                 const int mi = 2 * half + mh;
;                 f32x4 v = {acc[ni][mi][4 * g], acc[ni][mi][4 * g + 1], acc[ni][mi][4 * g + 2], acc[ni][mi][4 * g + 3]};
;                 *(f32x4*)(wl + (mh * 32 + l31) * 272 + (ni * 32 + 8 * g + 4 * hh) * 4) = v;
;               }
;           asm volatile("" ::: "memory");
; #pragma unroll
;           for (int i = 0; i < 16; ++i) {
;             const int row = (lane >> 4) + 4 * i, ch = lane & 15;
;             const f32x4 v = *(const f32x4*)(wl + row * 272 + ch * 16);
;             epi(m0 + half * 64 + row, n0 + ch * 4, v);
;           }
	v_pk_fma_f32 v[74:75], v[244:245], v[210:211], v[74:75]
	v_pk_fma_f32 v[72:73], v[242:243], v[208:209], v[72:73]
	global_store_dwordx4 v[240:241], v[72:75], off
	v_lshl_add_u64 v[240:241], v[240:241], 0, s[100:101]
	ds_read_b128 v[242:245], v192 offset:4352
	s_waitcnt vmcnt(15) lgkmcnt(1)
	v_pk_fma_f32 v[78:79], v[248:249], v[210:211], v[78:79]
	v_pk_fma_f32 v[76:77], v[246:247], v[208:209], v[76:77]
	global_store_dwordx4 v[240:241], v[76:79], off
	v_lshl_add_u64 v[240:241], v[240:241], 0, s[100:101]
	ds_read_b128 v[246:249], v192 offset:5440
	s_waitcnt vmcnt(15) lgkmcnt(1)
	v_pk_fma_f32 v[82:83], v[244:245], v[210:211], v[82:83]
	v_pk_fma_f32 v[80:81], v[242:243], v[208:209], v[80:81]
	global_store_dwordx4 v[240:241], v[80:83], off
	v_lshl_add_u64 v[240:241], v[240:241], 0, s[100:101]
	ds_read_b128 v[242:245], v192 offset:6528
	s_waitcnt vmcnt(15) lgkmcnt(1)
	v_pk_fma_f32 v[86:87], v[248:249], v[210:211], v[86:87]
	v_pk_fma_f32 v[84:85], v[246:247], v[208:209], v[84:85]
	global_store_dwordx4 v[240:241], v[84:87], off
	v_lshl_add_u64 v[240:241], v[240:241], 0, s[100:101]
	ds_read_b128 v[246:249], v192 offset:7616
	s_waitcnt vmcnt(15) lgkmcnt(1)
	v_pk_fma_f32 v[90:91], v[244:245], v[210:211], v[90:91]
	v_pk_fma_f32 v[88:89], v[242:243], v[208:209], v[88:89]
	global_store_dwordx4 v[240:241], v[88:91], off
	v_lshl_add_u64 v[240:241], v[240:241], 0, s[100:101]
	ds_read_b128 v[242:245], v192 offset:8704
	s_waitcnt vmcnt(15) lgkmcnt(1)
	v_pk_fma_f32 v[94:95], v[248:249], v[210:211], v[94:95]
	v_pk_fma_f32 v[92:93], v[246:247], v[208:209], v[92:93]
	global_store_dwordx4 v[240:241], v[92:95], off
	v_lshl_add_u64 v[240:241], v[240:241], 0, s[100:101]
	ds_read_b128 v[246:249], v192 offset:9792
	s_waitcnt vmcnt(15) lgkmcnt(1)
	v_pk_fma_f32 v[98:99], v[244:245], v[210:211], v[98:99]
	v_pk_fma_f32 v[96:97], v[242:243], v[208:209], v[96:97]
	global_store_dwordx4 v[240:241], v[96:99], off
	v_lshl_add_u64 v[240:241], v[240:241], 0, s[100:101]
	ds_read_b128 v[242:245], v192 offset:10880
	s_waitcnt vmcnt(15) lgkmcnt(1)
	v_pk_fma_f32 v[102:103], v[248:249], v[210:211], v[102:103]
	v_pk_fma_f32 v[100:101], v[246:247], v[208:209], v[100:101]
	global_store_dwordx4 v[240:241], v[100:103], off
	v_lshl_add_u64 v[240:241], v[240:241], 0, s[100:101]
	ds_read_b128 v[246:249], v192 offset:11968
	s_waitcnt vmcnt(15) lgkmcnt(1)
	v_pk_fma_f32 v[106:107], v[244:245], v[210:211], v[106:107]
	v_pk_fma_f32 v[104:105], v[242:243], v[208:209], v[104:105]
	global_store_dwordx4 v[240:241], v[104:107], off
	v_lshl_add_u64 v[240:241], v[240:241], 0, s[100:101]
	ds_read_b128 v[242:245], v192 offset:13056
	s_waitcnt vmcnt(15) lgkmcnt(1)
	v_pk_fma_f32 v[110:111], v[248:249], v[210:211], v[110:111]
	v_pk_fma_f32 v[108:109], v[246:247], v[208:209], v[108:109]
	global_store_dwordx4 v[240:241], v[108:111], off
	v_lshl_add_u64 v[240:241], v[240:241], 0, s[100:101]
	ds_read_b128 v[246:249], v192 offset:14144
	s_waitcnt vmcnt(15) lgkmcnt(1)
	v_pk_fma_f32 v[114:115], v[244:245], v[210:211], v[114:115]
	v_pk_fma_f32 v[112:113], v[242:243], v[208:209], v[112:113]
	global_store_dwordx4 v[240:241], v[112:115], off
	v_lshl_add_u64 v[240:241], v[240:241], 0, s[100:101]
	ds_read_b128 v[242:245], v192 offset:15232
	s_waitcnt vmcnt(15) lgkmcnt(1)
	v_pk_fma_f32 v[118:119], v[248:249], v[210:211], v[118:119]
	v_pk_fma_f32 v[116:117], v[246:247], v[208:209], v[116:117]
	global_store_dwordx4 v[240:241], v[116:119], off
	v_lshl_add_u64 v[240:241], v[240:241], 0, s[100:101]
	ds_read_b128 v[246:249], v192 offset:16320
	s_waitcnt vmcnt(15) lgkmcnt(1)
	v_pk_fma_f32 v[122:123], v[244:245], v[210:211], v[122:123]
	v_pk_fma_f32 v[120:121], v[242:243], v[208:209], v[120:121]
	global_store_dwordx4 v[240:241], v[120:123], off
	v_lshl_add_u64 v[240:241], v[240:241], 0, s[100:101]
	s_waitcnt vmcnt(15) lgkmcnt(0)
	v_pk_fma_f32 v[126:127], v[248:249], v[210:211], v[126:127]
	v_pk_fma_f32 v[124:125], v[246:247], v[208:209], v[124:125]
	global_store_dwordx4 v[240:241], v[124:127], off
	v_lshl_add_u64 v[240:241], v[240:241], 0, s[100:101]
	ds_write_b128 v191, v[48:51]
	ds_write_b128 v191, v[52:55] offset:32
	ds_write_b128 v191, v[56:59] offset:64
	ds_write_b128 v191, v[60:63] offset:96
	ds_write_b128 v191, v[32:35] offset:8704
	ds_write_b128 v191, v[36:39] offset:8736
	ds_write_b128 v191, v[40:43] offset:8768
	ds_write_b128 v191, v[44:47] offset:8800
	ds_write_b128 v191, v[16:19] offset:128
	ds_write_b128 v191, v[20:23] offset:160
	ds_write_b128 v191, v[24:27] offset:192
	ds_write_b128 v191, v[28:31] offset:224
	ds_write_b128 v191, v[0:3] offset:8832
	ds_write_b128 v191, v[4:7] offset:8864
	ds_write_b128 v191, v[8:11] offset:8896
	ds_write_b128 v191, v[12:15] offset:8928
	global_load_dwordx4 v[0:3], v[238:239], off
	v_lshl_add_u64 v[238:239], v[238:239], 0, s[100:101]
	global_load_dwordx4 v[4:7], v[238:239], off
	v_lshl_add_u64 v[238:239], v[238:239], 0, s[100:101]
	global_load_dwordx4 v[8:11], v[238:239], off
	v_lshl_add_u64 v[238:239], v[238:239], 0, s[100:101]
	global_load_dwordx4 v[12:15], v[238:239], off
	v_lshl_add_u64 v[238:239], v[238:239], 0, s[100:101]
	global_load_dwordx4 v[16:19], v[238:239], off
	v_lshl_add_u64 v[238:239], v[238:239], 0, s[100:101]
	global_load_dwordx4 v[20:23], v[238:239], off
	v_lshl_add_u64 v[238:239], v[238:239], 0, s[100:101]
	global_load_dwordx4 v[24:27], v[238:239], off
	v_lshl_add_u64 v[238:239], v[238:239], 0, s[100:101]
	global_load_dwordx4 v[28:31], v[238:239], off
	v_lshl_add_u64 v[238:239], v[238:239], 0, s[100:101]
	global_load_dwordx4 v[32:35], v[238:239], off
	v_lshl_add_u64 v[238:239], v[238:239], 0, s[100:101]
	global_load_dwordx4 v[36:39], v[238:239], off
	v_lshl_add_u64 v[238:239], v[238:239], 0, s[100:101]
	global_load_dwordx4 v[40:43], v[238:239], off
	v_lshl_add_u64 v[238:239], v[238:239], 0, s[100:101]
	global_load_dwordx4 v[44:47], v[238:239], off
	v_lshl_add_u64 v[238:239], v[238:239], 0, s[100:101]
	global_load_dwordx4 v[48:51], v[238:239], off
	v_lshl_add_u64 v[238:239], v[238:239], 0, s[100:101]
	global_load_dwordx4 v[52:55], v[238:239], off
	v_lshl_add_u64 v[238:239], v[238:239], 0, s[100:101]
	global_load_dwordx4 v[56:59], v[238:239], off
	v_lshl_add_u64 v[238:239], v[238:239], 0, s[100:101]
	global_load_dwordx4 v[60:63], v[238:239], off
	v_lshl_add_u64 v[238:239], v[238:239], 0, s[100:101]
	ds_read_b128 v[242:245], v192
	ds_read_b128 v[246:249], v192 offset:1088
	s_waitcnt vmcnt(15) lgkmcnt(1)
;   DI void operator()(int m, int n, f32x4 v) const {
;     const int row = m + row0;
;     const float* s = row < TL ? sl + (size_t)row * DM : sc + (size_t)(row - TL) * DM;
;     float* d = row < TL ? dl + (size_t)row * DM : dc + (size_t)(row - TL) * DM;
;     const int mi = row < TL ? (row >> 14) : 2;
;     const f32x4 g = *(const f32x4*)(gate + mi * 6144 + n);
;     const f32x4 r = *(const f32x4*)(s + n);
;     f32x4 o;
; #pragma unroll
;     for (int j = 0; j < 4; ++j) o[j] = r[j] + g[j] * v[j];
;     *(f32x4*)(d + n) = o;
;   }
; template <class Epi>
; DI void gemm_phase512(const bf16_t* A, const bf16_t* Bt, int mtiles, int ntiles, int K, int Kper, int ksplit, const Epi& epi,
;                       unsigned char* smem, int bid, int nb) {
;     ...
;           asm volatile("" ::: "memory");
; #pragma unroll
;           for (int i = 0; i < 16; ++i) {
;             const int row = (lane >> 4) + 4 * i, ch = lane & 15;
;             const f32x4 v = *(const f32x4*)(wl + row * 272 + ch * 16);
;             epi(m0 + half * 64 + row, n0 + ch * 4, v);
;           }
;         }
;       }
;     }
;     __syncthreads();
;     if (!more) break;
	v_pk_fma_f32 v[2:3], v[244:245], v[210:211], v[2:3]
	v_pk_fma_f32 v[0:1], v[242:243], v[208:209], v[0:1]
	global_store_dwordx4 v[240:241], v[0:3], off
	v_lshl_add_u64 v[240:241], v[240:241], 0, s[100:101]
	ds_read_b128 v[242:245], v192 offset:2176
	s_waitcnt vmcnt(15) lgkmcnt(1)
	v_pk_fma_f32 v[6:7], v[248:249], v[210:211], v[6:7]
	v_pk_fma_f32 v[4:5], v[246:247], v[208:209], v[4:5]
	global_store_dwordx4 v[240:241], v[4:7], off
	v_lshl_add_u64 v[240:241], v[240:241], 0, s[100:101]
	ds_read_b128 v[246:249], v192 offset:3264
	s_waitcnt vmcnt(15) lgkmcnt(1)
	v_pk_fma_f32 v[10:11], v[244:245], v[210:211], v[10:11]
	v_pk_fma_f32 v[8:9], v[242:243], v[208:209], v[8:9]
	global_store_dwordx4 v[240:241], v[8:11], off
	v_lshl_add_u64 v[240:241], v[240:241], 0, s[100:101]
	ds_read_b128 v[242:245], v192 offset:4352
	s_waitcnt vmcnt(15) lgkmcnt(1)
	v_pk_fma_f32 v[14:15], v[248:249], v[210:211], v[14:15]
	v_pk_fma_f32 v[12:13], v[246:247], v[208:209], v[12:13]
	global_store_dwordx4 v[240:241], v[12:15], off
	v_lshl_add_u64 v[240:241], v[240:241], 0, s[100:101]
	ds_read_b128 v[246:249], v192 offset:5440
	s_waitcnt vmcnt(15) lgkmcnt(1)
	v_pk_fma_f32 v[18:19], v[244:245], v[210:211], v[18:19]
	v_pk_fma_f32 v[16:17], v[242:243], v[208:209], v[16:17]
	global_store_dwordx4 v[240:241], v[16:19], off
	v_lshl_add_u64 v[240:241], v[240:241], 0, s[100:101]
	ds_read_b128 v[242:245], v192 offset:6528
	s_waitcnt vmcnt(15) lgkmcnt(1)
	v_pk_fma_f32 v[22:23], v[248:249], v[210:211], v[22:23]
	v_pk_fma_f32 v[20:21], v[246:247], v[208:209], v[20:21]
	global_store_dwordx4 v[240:241], v[20:23], off
	v_lshl_add_u64 v[240:241], v[240:241], 0, s[100:101]
	ds_read_b128 v[246:249], v192 offset:7616
	s_waitcnt vmcnt(15) lgkmcnt(1)
	v_pk_fma_f32 v[26:27], v[244:245], v[210:211], v[26:27]
	v_pk_fma_f32 v[24:25], v[242:243], v[208:209], v[24:25]
	global_store_dwordx4 v[240:241], v[24:27], off
	v_lshl_add_u64 v[240:241], v[240:241], 0, s[100:101]
	ds_read_b128 v[242:245], v192 offset:8704
	s_waitcnt vmcnt(15) lgkmcnt(1)
	v_pk_fma_f32 v[30:31], v[248:249], v[210:211], v[30:31]
	v_pk_fma_f32 v[28:29], v[246:247], v[208:209], v[28:29]
	global_store_dwordx4 v[240:241], v[28:31], off
	v_lshl_add_u64 v[240:241], v[240:241], 0, s[100:101]
	ds_read_b128 v[246:249], v192 offset:9792
	s_waitcnt vmcnt(15) lgkmcnt(1)
	v_pk_fma_f32 v[34:35], v[244:245], v[210:211], v[34:35]
	v_pk_fma_f32 v[32:33], v[242:243], v[208:209], v[32:33]
	global_store_dwordx4 v[240:241], v[32:35], off
	v_lshl_add_u64 v[240:241], v[240:241], 0, s[100:101]
	ds_read_b128 v[242:245], v192 offset:10880
	s_waitcnt vmcnt(15) lgkmcnt(1)
	v_pk_fma_f32 v[38:39], v[248:249], v[210:211], v[38:39]
	v_pk_fma_f32 v[36:37], v[246:247], v[208:209], v[36:37]
	global_store_dwordx4 v[240:241], v[36:39], off
	v_lshl_add_u64 v[240:241], v[240:241], 0, s[100:101]
	ds_read_b128 v[246:249], v192 offset:11968
	s_waitcnt vmcnt(15) lgkmcnt(1)
	v_pk_fma_f32 v[42:43], v[244:245], v[210:211], v[42:43]
	v_pk_fma_f32 v[40:41], v[242:243], v[208:209], v[40:41]
	global_store_dwordx4 v[240:241], v[40:43], off
	v_lshl_add_u64 v[240:241], v[240:241], 0, s[100:101]
	ds_read_b128 v[242:245], v192 offset:13056
	s_waitcnt vmcnt(15) lgkmcnt(1)
	v_pk_fma_f32 v[46:47], v[248:249], v[210:211], v[46:47]
	v_pk_fma_f32 v[44:45], v[246:247], v[208:209], v[44:45]
	global_store_dwordx4 v[240:241], v[44:47], off
	v_lshl_add_u64 v[240:241], v[240:241], 0, s[100:101]
	ds_read_b128 v[246:249], v192 offset:14144
	s_waitcnt vmcnt(15) lgkmcnt(1)
	v_pk_fma_f32 v[50:51], v[244:245], v[210:211], v[50:51]
	v_pk_fma_f32 v[48:49], v[242:243], v[208:209], v[48:49]
	global_store_dwordx4 v[240:241], v[48:51], off
	v_lshl_add_u64 v[240:241], v[240:241], 0, s[100:101]
	ds_read_b128 v[242:245], v192 offset:15232
	s_waitcnt vmcnt(15) lgkmcnt(1)
	v_pk_fma_f32 v[54:55], v[248:249], v[210:211], v[54:55]
	v_pk_fma_f32 v[52:53], v[246:247], v[208:209], v[52:53]
	global_store_dwordx4 v[240:241], v[52:55], off
	v_lshl_add_u64 v[240:241], v[240:241], 0, s[100:101]
	ds_read_b128 v[246:249], v192 offset:16320
	s_waitcnt vmcnt(15) lgkmcnt(1)
	v_pk_fma_f32 v[58:59], v[244:245], v[210:211], v[58:59]
	v_pk_fma_f32 v[56:57], v[242:243], v[208:209], v[56:57]
	global_store_dwordx4 v[240:241], v[56:59], off
	v_lshl_add_u64 v[240:241], v[240:241], 0, s[100:101]
	s_waitcnt vmcnt(15) lgkmcnt(0)
	v_pk_fma_f32 v[62:63], v[248:249], v[210:211], v[62:63]
	v_pk_fma_f32 v[60:61], v[246:247], v[208:209], v[60:61]
	global_store_dwordx4 v[240:241], v[60:63], off
	v_lshl_add_u64 v[240:241], v[240:241], 0, s[100:101]
	s_andn2_b64 vcc, exec, s[2:3]
	s_barrier
	s_cbranch_vccz .LBB0_586

;   DI void operator()(int m, int n, f32x4 v) const {
;     const int row = m + row0;
;     const float* s = row < TL ? sl + (size_t)row * DM : sc + (size_t)(row - TL) * DM;
;     float* d = row < TL ? dl + (size_t)row * DM : dc + (size_t)(row - TL) * DM;
;     const int mi = row < TL ? (row >> 14) : 2;
;     const f32x4 g = *(const f32x4*)(gate + mi * 6144 + n);
;     const f32x4 r = *(const f32x4*)(s + n);
;     f32x4 o;
; #pragma unroll
;     for (int j = 0; j < 4; ++j) o[j] = r[j] + g[j] * v[j];
;     *(f32x4*)(d + n) = o;
;   }
; template <class Epi>
; DI void gemm_phase512(const bf16_t* A, const bf16_t* Bt, int mtiles, int ntiles, int K, int Kper, int ksplit, const Epi& epi,
;                       unsigned char* smem, int bid, int nb) {
;     ...
;       } else {
; #pragma unroll
;         for (int half = 0; half < 2; ++half) {
;           if (half) asm volatile("" ::: "memory");
; #pragma unroll
;           for (int ni = 0; ni < 2; ++ni)
; #pragma unroll
;             for (int mh = 0; mh < 2; ++mh)
; #pragma unroll
;               for (int g = 0; g < 4; ++g) {
;                 const int mi = 2 * half + mh;
;                 f32x4 v = {acc[ni][mi][4 * g], acc[ni][mi][4 * g + 1], acc[ni][mi][4 * g + 2], acc[ni][mi][4 * g + 3]};
;                 *(f32x4*)(wl + (mh * 32 + l31) * 272 + (ni * 32 + 8 * g + 4 * hh) * 4) = v;
;               }
;           asm volatile("" ::: "memory");
; #pragma unroll
;           for (int i = 0; i < 16; ++i) {
;             const int row = (lane >> 4) + 4 * i, ch = lane & 15;
;             const f32x4 v = *(const f32x4*)(wl + row * 272 + ch * 16);
;             epi(m0 + half * 64 + row, n0 + ch * 4, v);
;           }
.LBB0_771:
	s_waitcnt vmcnt(5)
	v_add_co_u32_e32 v132, vcc, 0x80000, v164
	v_lshl_or_b32 v197, s26, 8, v171
	s_nop 0
	v_addc_co_u32_e32 v133, vcc, 0, v165, vcc
	s_waitcnt vmcnt(4)
	v_add_co_u32_e32 v136, vcc, 0x80000, v168
	global_load_dwordx4 v[128:131], v[164:165], off
	s_nop 0
	v_addc_co_u32_e32 v137, vcc, 0, v169, vcc
	s_waitcnt vmcnt(4)
	v_add_co_u32_e32 v140, vcc, 0x100000, v164
	global_load_dwordx4 v[132:135], v[132:133], off
	s_nop 0
	v_addc_co_u32_e32 v141, vcc, 0, v165, vcc
	s_waitcnt vmcnt(4)
	v_add_co_u32_e32 v144, vcc, 0x100000, v168
	global_load_dwordx4 v[136:139], v[136:137], off
	s_nop 0
	v_addc_co_u32_e32 v145, vcc, 0, v169, vcc
	v_add_co_u32_e32 v148, vcc, 0x180000, v164
	global_load_dwordx4 v[140:143], v[140:141], off
	s_nop 0
	v_addc_co_u32_e32 v149, vcc, 0, v165, vcc
	s_waitcnt vmcnt(5)
	v_add_co_u32_e32 v152, vcc, 0x180000, v168
	global_load_dwordx4 v[144:147], v[144:145], off
	s_nop 0
	v_addc_co_u32_e32 v153, vcc, 0, v169, vcc
	global_load_dwordx4 v[148:151], v[148:149], off
	s_nop 0
	global_load_dwordx4 v[156:159], v[168:169], off
	s_nop 0
	global_load_dwordx4 v[152:155], v[152:153], off
	ds_write_b128 v191, v[112:115]
	ds_write_b128 v191, v[116:119] offset:32
	ds_write_b128 v191, v[120:123] offset:64
	ds_write_b128 v191, v[124:127] offset:96
	ds_write_b128 v191, v[96:99] offset:8704
	ds_write_b128 v191, v[100:103] offset:8736
	ds_write_b128 v191, v[104:107] offset:8768
	ds_write_b128 v191, v[108:111] offset:8800
	ds_write_b128 v191, v[80:83] offset:128
	ds_write_b128 v191, v[84:87] offset:160
	ds_write_b128 v191, v[88:91] offset:192
	ds_write_b128 v191, v[92:95] offset:224
	ds_write_b128 v191, v[64:67] offset:8832
	ds_write_b128 v191, v[68:71] offset:8864
	ds_write_b128 v191, v[72:75] offset:8896
	ds_write_b128 v191, v[76:79] offset:8928
	v_lshl_add_u32 v198, s25, 8, v173
	v_ashrrev_i32_e32 v199, 31, v198
	v_or_b32_e32 v200, v197, v172
	v_add_u32_e32 v200, s46, v200
	v_lshlrev_b64 v[198:199], 2, v[198:199]
	v_cmp_gt_i32_e32 vcc, s34, v200
	v_add_u32_e32 v202, 0xffff8000, v200
	v_ashrrev_i32_e32 v203, 31, v200
	v_min_i32_e32 v204, 0x8000, v200
	v_cndmask_b32_e32 v203, 0, v203, vcc
	v_cndmask_b32_e32 v202, v202, v200, vcc
	v_ashrrev_i32_e32 v204, 14, v204
	v_lshlrev_b64 v[202:203], 12, v[202:203]
	v_mul_i32_i24_e32 v204, 0x1800, v204
	v_ashrrev_i32_e32 v205, 31, v204
	v_lshl_add_u64 v[206:207], v[204:205], 2, s[40:41]
	v_lshl_add_u64 v[206:207], v[206:207], 0, v[198:199]
	global_load_dwordx4 v[208:211], v[206:207], off
	v_mov_b32_e32 v239, s7
	v_mov_b32_e32 v201, s5
	v_mov_b32_e32 v238, s6
	v_mov_b32_e32 v200, s4
	v_cndmask_b32_e32 v239, v239, v201, vcc
	v_cndmask_b32_e32 v238, v238, v200, vcc
	v_mov_b32_e32 v241, s7
	v_mov_b32_e32 v201, s5
	v_mov_b32_e32 v240, s6
	v_mov_b32_e32 v200, s4
	v_cndmask_b32_e32 v241, v241, v201, vcc
	v_cndmask_b32_e32 v240, v240, v200, vcc
	v_lshl_add_u64 v[238:239], v[238:239], 0, v[202:203]
	v_lshl_add_u64 v[240:241], v[240:241], 0, v[202:203]
	v_lshl_add_u64 v[238:239], v[238:239], 0, v[198:199]
	v_lshl_add_u64 v[240:241], v[240:241], 0, v[198:199]
	s_mov_b32 s25, s22
	s_mov_b32 s26, s24
	s_mov_b32 s100, 0x4000
	s_mov_b32 s101, 0
	global_load_dwordx4 v[64:67], v[238:239], off
	v_lshl_add_u64 v[238:239], v[238:239], 0, s[100:101]
	global_load_dwordx4 v[68:71], v[238:239], off
	v_lshl_add_u64 v[238:239], v[238:239], 0, s[100:101]
	global_load_dwordx4 v[72:75], v[238:239], off
	v_lshl_add_u64 v[238:239], v[238:239], 0, s[100:101]
	global_load_dwordx4 v[76:79], v[238:239], off
	v_lshl_add_u64 v[238:239], v[238:239], 0, s[100:101]
	global_load_dwordx4 v[80:83], v[238:239], off
	v_lshl_add_u64 v[238:239], v[238:239], 0, s[100:101]
	global_load_dwordx4 v[84:87], v[238:239], off
	v_lshl_add_u64 v[238:239], v[238:239], 0, s[100:101]
	global_load_dwordx4 v[88:91], v[238:239], off
	v_lshl_add_u64 v[238:239], v[238:239], 0, s[100:101]
	global_load_dwordx4 v[92:95], v[238:239], off
	v_lshl_add_u64 v[238:239], v[238:239], 0, s[100:101]
	global_load_dwordx4 v[96:99], v[238:239], off
	v_lshl_add_u64 v[238:239], v[238:239], 0, s[100:101]
	global_load_dwordx4 v[100:103], v[238:239], off
	v_lshl_add_u64 v[238:239], v[238:239], 0, s[100:101]
	global_load_dwordx4 v[104:107], v[238:239], off
	v_lshl_add_u64 v[238:239], v[238:239], 0, s[100:101]
	global_load_dwordx4 v[108:111], v[238:239], off
	v_lshl_add_u64 v[238:239], v[238:239], 0, s[100:101]
	global_load_dwordx4 v[112:115], v[238:239], off
	v_lshl_add_u64 v[238:239], v[238:239], 0, s[100:101]
	global_load_dwordx4 v[116:119], v[238:239], off
	v_lshl_add_u64 v[238:239], v[238:239], 0, s[100:101]
	global_load_dwordx4 v[120:123], v[238:239], off
	v_lshl_add_u64 v[238:239], v[238:239], 0, s[100:101]
	global_load_dwordx4 v[124:127], v[238:239], off
	v_lshl_add_u64 v[238:239], v[238:239], 0, s[100:101]
	ds_read_b128 v[242:245], v192
	ds_read_b128 v[246:249], v192 offset:1088
	s_waitcnt vmcnt(15) lgkmcnt(1)
	v_pk_fma_f32 v[66:67], v[244:245], v[210:211], v[66:67]
	v_pk_fma_f32 v[64:65], v[242:243], v[208:209], v[64:65]
	global_store_dwordx4 v[240:241], v[64:67], off
	v_lshl_add_u64 v[240:241], v[240:241], 0, s[100:101]
	ds_read_b128 v[242:245], v192 offset:2176
	s_waitcnt vmcnt(15) lgkmcnt(1)
	v_pk_fma_f32 v[70:71], v[248:249], v[210:211], v[70:71]
	v_pk_fma_f32 v[68:69], v[246:247], v[208:209], v[68:69]
	global_store_dwordx4 v[240:241], v[68:71], off
	v_lshl_add_u64 v[240:241], v[240:241], 0, s[100:101]
	ds_read_b128 v[246:249], v192 offset:3264
	s_waitcnt vmcnt(15) lgkmcnt(1)
	v_pk_fma_f32 v[74:75], v[244:245], v[210:211], v[74:75]
	v_pk_fma_f32 v[72:73], v[242:243], v[208:209], v[72:73]
	global_store_dwordx4 v[240:241], v[72:75], off
	v_lshl_add_u64 v[240:241], v[240:241], 0, s[100:101]
	ds_read_b128 v[242:245], v192 offset:4352
	s_waitcnt vmcnt(15) lgkmcnt(1)
;   DI void operator()(int m, int n, f32x4 v) const {
;     const int row = m + row0;
;     const float* s = row < TL ? sl + (size_t)row * DM : sc + (size_t)(row - TL) * DM;
;     float* d = row < TL ? dl + (size_t)row * DM : dc + (size_t)(row - TL) * DM;
;     const int mi = row < TL ? (row >> 14) : 2;
;     const f32x4 g = *(const f32x4*)(gate + mi * 6144 + n);
;     const f32x4 r = *(const f32x4*)(s + n);
;     f32x4 o;
; #pragma unroll
;     for (int j = 0; j < 4; ++j) o[j] = r[j] + g[j] * v[j];
;     *(f32x4*)(d + n) = o;
;   }
; template <class Epi>
; DI void gemm_phase512(const bf16_t* A, const bf16_t* Bt, int mtiles, int ntiles, int K, int Kper, int ksplit, const Epi& epi,
;                       unsigned char* smem, int bid, int nb) {
;     ...
;         for (int half = 0; half < 2; ++half) {
;           if (half) asm volatile("" ::: "memory");
; #pragma unroll
;           for (int ni = 0; ni < 2; ++ni)
; #pragma unroll
;             for (int mh = 0; mh < 2; ++mh)
; #pragma unroll
;               for (int g = 0; g < 4; ++g) {
;                 const int mi = 2 * half + mh;
;                 f32x4 v = {acc[ni][mi][4 * g], acc[ni][mi][4 * g + 1], acc[ni][mi][4 * g + 2], acc[ni][mi][4 * g + 3]};
;                 *(f32x4*)(wl + (mh * 32 + l31) * 272 + (ni * 32 + 8 * g + 4 * hh) * 4) = v;
;               }
;           asm volatile("" ::: "memory");
; #pragma unroll
;           for (int i = 0; i < 16; ++i) {
;             const int row = (lane >> 4) + 4 * i, ch = lane & 15;
;             const f32x4 v = *(const f32x4*)(wl + row * 272 + ch * 16);
;             epi(m0 + half * 64 + row, n0 + ch * 4, v);
;           }
	v_pk_fma_f32 v[78:79], v[248:249], v[210:211], v[78:79]
	v_pk_fma_f32 v[76:77], v[246:247], v[208:209], v[76:77]
	global_store_dwordx4 v[240:241], v[76:79], off
	v_lshl_add_u64 v[240:241], v[240:241], 0, s[100:101]
	ds_read_b128 v[246:249], v192 offset:5440
	s_waitcnt vmcnt(15) lgkmcnt(1)
	v_pk_fma_f32 v[82:83], v[244:245], v[210:211], v[82:83]
	v_pk_fma_f32 v[80:81], v[242:243], v[208:209], v[80:81]
	global_store_dwordx4 v[240:241], v[80:83], off
	v_lshl_add_u64 v[240:241], v[240:241], 0, s[100:101]
	ds_read_b128 v[242:245], v192 offset:6528
	s_waitcnt vmcnt(15) lgkmcnt(1)
	v_pk_fma_f32 v[86:87], v[248:249], v[210:211], v[86:87]
	v_pk_fma_f32 v[84:85], v[246:247], v[208:209], v[84:85]
	global_store_dwordx4 v[240:241], v[84:87], off
	v_lshl_add_u64 v[240:241], v[240:241], 0, s[100:101]
	ds_read_b128 v[246:249], v192 offset:7616
	s_waitcnt vmcnt(15) lgkmcnt(1)
	v_pk_fma_f32 v[90:91], v[244:245], v[210:211], v[90:91]
	v_pk_fma_f32 v[88:89], v[242:243], v[208:209], v[88:89]
	global_store_dwordx4 v[240:241], v[88:91], off
	v_lshl_add_u64 v[240:241], v[240:241], 0, s[100:101]
	ds_read_b128 v[242:245], v192 offset:8704
	s_waitcnt vmcnt(15) lgkmcnt(1)
	v_pk_fma_f32 v[94:95], v[248:249], v[210:211], v[94:95]
	v_pk_fma_f32 v[92:93], v[246:247], v[208:209], v[92:93]
	global_store_dwordx4 v[240:241], v[92:95], off
	v_lshl_add_u64 v[240:241], v[240:241], 0, s[100:101]
	ds_read_b128 v[246:249], v192 offset:9792
	s_waitcnt vmcnt(15) lgkmcnt(1)
	v_pk_fma_f32 v[98:99], v[244:245], v[210:211], v[98:99]
	v_pk_fma_f32 v[96:97], v[242:243], v[208:209], v[96:97]
	global_store_dwordx4 v[240:241], v[96:99], off
	v_lshl_add_u64 v[240:241], v[240:241], 0, s[100:101]
	ds_read_b128 v[242:245], v192 offset:10880
	s_waitcnt vmcnt(15) lgkmcnt(1)
	v_pk_fma_f32 v[102:103], v[248:249], v[210:211], v[102:103]
	v_pk_fma_f32 v[100:101], v[246:247], v[208:209], v[100:101]
	global_store_dwordx4 v[240:241], v[100:103], off
	v_lshl_add_u64 v[240:241], v[240:241], 0, s[100:101]
	ds_read_b128 v[246:249], v192 offset:11968
	s_waitcnt vmcnt(15) lgkmcnt(1)
	v_pk_fma_f32 v[106:107], v[244:245], v[210:211], v[106:107]
	v_pk_fma_f32 v[104:105], v[242:243], v[208:209], v[104:105]
	global_store_dwordx4 v[240:241], v[104:107], off
	v_lshl_add_u64 v[240:241], v[240:241], 0, s[100:101]
	ds_read_b128 v[242:245], v192 offset:13056
	s_waitcnt vmcnt(15) lgkmcnt(1)
	v_pk_fma_f32 v[110:111], v[248:249], v[210:211], v[110:111]
	v_pk_fma_f32 v[108:109], v[246:247], v[208:209], v[108:109]
	global_store_dwordx4 v[240:241], v[108:111], off
	v_lshl_add_u64 v[240:241], v[240:241], 0, s[100:101]
	ds_read_b128 v[246:249], v192 offset:14144
	s_waitcnt vmcnt(15) lgkmcnt(1)
	v_pk_fma_f32 v[114:115], v[244:245], v[210:211], v[114:115]
	v_pk_fma_f32 v[112:113], v[242:243], v[208:209], v[112:113]
	global_store_dwordx4 v[240:241], v[112:115], off
	v_lshl_add_u64 v[240:241], v[240:241], 0, s[100:101]
	ds_read_b128 v[242:245], v192 offset:15232
	s_waitcnt vmcnt(15) lgkmcnt(1)
	v_pk_fma_f32 v[118:119], v[248:249], v[210:211], v[118:119]
	v_pk_fma_f32 v[116:117], v[246:247], v[208:209], v[116:117]
	global_store_dwordx4 v[240:241], v[116:119], off
	v_lshl_add_u64 v[240:241], v[240:241], 0, s[100:101]
	ds_read_b128 v[246:249], v192 offset:16320
	s_waitcnt vmcnt(15) lgkmcnt(1)
	v_pk_fma_f32 v[122:123], v[244:245], v[210:211], v[122:123]
	v_pk_fma_f32 v[120:121], v[242:243], v[208:209], v[120:121]
	global_store_dwordx4 v[240:241], v[120:123], off
	v_lshl_add_u64 v[240:241], v[240:241], 0, s[100:101]
	s_waitcnt vmcnt(15) lgkmcnt(0)
	v_pk_fma_f32 v[126:127], v[248:249], v[210:211], v[126:127]
	v_pk_fma_f32 v[124:125], v[246:247], v[208:209], v[124:125]
	global_store_dwordx4 v[240:241], v[124:127], off
	v_lshl_add_u64 v[240:241], v[240:241], 0, s[100:101]
	ds_write_b128 v191, v[48:51]
	ds_write_b128 v191, v[52:55] offset:32
	ds_write_b128 v191, v[56:59] offset:64
	ds_write_b128 v191, v[60:63] offset:96
	ds_write_b128 v191, v[32:35] offset:8704
	ds_write_b128 v191, v[36:39] offset:8736
	ds_write_b128 v191, v[40:43] offset:8768
	ds_write_b128 v191, v[44:47] offset:8800
	ds_write_b128 v191, v[16:19] offset:128
	ds_write_b128 v191, v[20:23] offset:160
	ds_write_b128 v191, v[24:27] offset:192
	ds_write_b128 v191, v[28:31] offset:224
	ds_write_b128 v191, v[0:3] offset:8832
	ds_write_b128 v191, v[4:7] offset:8864
	ds_write_b128 v191, v[8:11] offset:8896
	ds_write_b128 v191, v[12:15] offset:8928
	global_load_dwordx4 v[0:3], v[238:239], off
	v_lshl_add_u64 v[238:239], v[238:239], 0, s[100:101]
	global_load_dwordx4 v[4:7], v[238:239], off
	v_lshl_add_u64 v[238:239], v[238:239], 0, s[100:101]
	global_load_dwordx4 v[8:11], v[238:239], off
	v_lshl_add_u64 v[238:239], v[238:239], 0, s[100:101]
	global_load_dwordx4 v[12:15], v[238:239], off
	v_lshl_add_u64 v[238:239], v[238:239], 0, s[100:101]
	global_load_dwordx4 v[16:19], v[238:239], off
	v_lshl_add_u64 v[238:239], v[238:239], 0, s[100:101]
	global_load_dwordx4 v[20:23], v[238:239], off
	v_lshl_add_u64 v[238:239], v[238:239], 0, s[100:101]
	global_load_dwordx4 v[24:27], v[238:239], off
	v_lshl_add_u64 v[238:239], v[238:239], 0, s[100:101]
	global_load_dwordx4 v[28:31], v[238:239], off
	v_lshl_add_u64 v[238:239], v[238:239], 0, s[100:101]
	global_load_dwordx4 v[32:35], v[238:239], off
	v_lshl_add_u64 v[238:239], v[238:239], 0, s[100:101]
	global_load_dwordx4 v[36:39], v[238:239], off
	v_lshl_add_u64 v[238:239], v[238:239], 0, s[100:101]
	global_load_dwordx4 v[40:43], v[238:239], off
	v_lshl_add_u64 v[238:239], v[238:239], 0, s[100:101]
	global_load_dwordx4 v[44:47], v[238:239], off
	v_lshl_add_u64 v[238:239], v[238:239], 0, s[100:101]
	global_load_dwordx4 v[48:51], v[238:239], off
	v_lshl_add_u64 v[238:239], v[238:239], 0, s[100:101]
	global_load_dwordx4 v[52:55], v[238:239], off
	v_lshl_add_u64 v[238:239], v[238:239], 0, s[100:101]
	global_load_dwordx4 v[56:59], v[238:239], off
	v_lshl_add_u64 v[238:239], v[238:239], 0, s[100:101]
	global_load_dwordx4 v[60:63], v[238:239], off
	v_lshl_add_u64 v[238:239], v[238:239], 0, s[100:101]
	ds_read_b128 v[242:245], v192
	ds_read_b128 v[246:249], v192 offset:1088
	s_waitcnt vmcnt(15) lgkmcnt(1)
;   DI void operator()(int m, int n, f32x4 v) const {
;     const int row = m + row0;
;     const float* s = row < TL ? sl + (size_t)row * DM : sc + (size_t)(row - TL) * DM;
;     float* d = row < TL ? dl + (size_t)row * DM : dc + (size_t)(row - TL) * DM;
;     const int mi = row < TL ? (row >> 14) : 2;
;     const f32x4 g = *(const f32x4*)(gate + mi * 6144 + n);
;     const f32x4 r = *(const f32x4*)(s + n);
;     f32x4 o;
; #pragma unroll
;     for (int j = 0; j < 4; ++j) o[j] = r[j] + g[j] * v[j];
;     *(f32x4*)(d + n) = o;
;   }
; template <class Epi>
; DI void gemm_phase512(const bf16_t* A, const bf16_t* Bt, int mtiles, int ntiles, int K, int Kper, int ksplit, const Epi& epi,
;                       unsigned char* smem, int bid, int nb) {
;     ...
;           asm volatile("" ::: "memory");
; #pragma unroll
;           for (int i = 0; i < 16; ++i) {
;             const int row = (lane >> 4) + 4 * i, ch = lane & 15;
;             const f32x4 v = *(const f32x4*)(wl + row * 272 + ch * 16);
;             epi(m0 + half * 64 + row, n0 + ch * 4, v);
;           }
;         }
;       }
;     }
;     __syncthreads();
;     if (!more) break;
	v_pk_fma_f32 v[2:3], v[244:245], v[210:211], v[2:3]
	v_pk_fma_f32 v[0:1], v[242:243], v[208:209], v[0:1]
	global_store_dwordx4 v[240:241], v[0:3], off
	v_lshl_add_u64 v[240:241], v[240:241], 0, s[100:101]
	ds_read_b128 v[242:245], v192 offset:2176
	s_waitcnt vmcnt(15) lgkmcnt(1)
	v_pk_fma_f32 v[6:7], v[248:249], v[210:211], v[6:7]
	v_pk_fma_f32 v[4:5], v[246:247], v[208:209], v[4:5]
	global_store_dwordx4 v[240:241], v[4:7], off
	v_lshl_add_u64 v[240:241], v[240:241], 0, s[100:101]
	ds_read_b128 v[246:249], v192 offset:3264
	s_waitcnt vmcnt(15) lgkmcnt(1)
	v_pk_fma_f32 v[10:11], v[244:245], v[210:211], v[10:11]
	v_pk_fma_f32 v[8:9], v[242:243], v[208:209], v[8:9]
	global_store_dwordx4 v[240:241], v[8:11], off
	v_lshl_add_u64 v[240:241], v[240:241], 0, s[100:101]
	ds_read_b128 v[242:245], v192 offset:4352
	s_waitcnt vmcnt(15) lgkmcnt(1)
	v_pk_fma_f32 v[14:15], v[248:249], v[210:211], v[14:15]
	v_pk_fma_f32 v[12:13], v[246:247], v[208:209], v[12:13]
	global_store_dwordx4 v[240:241], v[12:15], off
	v_lshl_add_u64 v[240:241], v[240:241], 0, s[100:101]
	ds_read_b128 v[246:249], v192 offset:5440
	s_waitcnt vmcnt(15) lgkmcnt(1)
	v_pk_fma_f32 v[18:19], v[244:245], v[210:211], v[18:19]
	v_pk_fma_f32 v[16:17], v[242:243], v[208:209], v[16:17]
	global_store_dwordx4 v[240:241], v[16:19], off
	v_lshl_add_u64 v[240:241], v[240:241], 0, s[100:101]
	ds_read_b128 v[242:245], v192 offset:6528
	s_waitcnt vmcnt(15) lgkmcnt(1)
	v_pk_fma_f32 v[22:23], v[248:249], v[210:211], v[22:23]
	v_pk_fma_f32 v[20:21], v[246:247], v[208:209], v[20:21]
	global_store_dwordx4 v[240:241], v[20:23], off
	v_lshl_add_u64 v[240:241], v[240:241], 0, s[100:101]
	ds_read_b128 v[246:249], v192 offset:7616
	s_waitcnt vmcnt(15) lgkmcnt(1)
	v_pk_fma_f32 v[26:27], v[244:245], v[210:211], v[26:27]
	v_pk_fma_f32 v[24:25], v[242:243], v[208:209], v[24:25]
	global_store_dwordx4 v[240:241], v[24:27], off
	v_lshl_add_u64 v[240:241], v[240:241], 0, s[100:101]
	ds_read_b128 v[242:245], v192 offset:8704
	s_waitcnt vmcnt(15) lgkmcnt(1)
	v_pk_fma_f32 v[30:31], v[248:249], v[210:211], v[30:31]
	v_pk_fma_f32 v[28:29], v[246:247], v[208:209], v[28:29]
	global_store_dwordx4 v[240:241], v[28:31], off
	v_lshl_add_u64 v[240:241], v[240:241], 0, s[100:101]
	ds_read_b128 v[246:249], v192 offset:9792
	s_waitcnt vmcnt(15) lgkmcnt(1)
	v_pk_fma_f32 v[34:35], v[244:245], v[210:211], v[34:35]
	v_pk_fma_f32 v[32:33], v[242:243], v[208:209], v[32:33]
	global_store_dwordx4 v[240:241], v[32:35], off
	v_lshl_add_u64 v[240:241], v[240:241], 0, s[100:101]
	ds_read_b128 v[242:245], v192 offset:10880
	s_waitcnt vmcnt(15) lgkmcnt(1)
	v_pk_fma_f32 v[38:39], v[248:249], v[210:211], v[38:39]
	v_pk_fma_f32 v[36:37], v[246:247], v[208:209], v[36:37]
	global_store_dwordx4 v[240:241], v[36:39], off
	v_lshl_add_u64 v[240:241], v[240:241], 0, s[100:101]
	ds_read_b128 v[246:249], v192 offset:11968
	s_waitcnt vmcnt(15) lgkmcnt(1)
	v_pk_fma_f32 v[42:43], v[244:245], v[210:211], v[42:43]
	v_pk_fma_f32 v[40:41], v[242:243], v[208:209], v[40:41]
	global_store_dwordx4 v[240:241], v[40:43], off
	v_lshl_add_u64 v[240:241], v[240:241], 0, s[100:101]
	ds_read_b128 v[242:245], v192 offset:13056
	s_waitcnt vmcnt(15) lgkmcnt(1)
	v_pk_fma_f32 v[46:47], v[248:249], v[210:211], v[46:47]
	v_pk_fma_f32 v[44:45], v[246:247], v[208:209], v[44:45]
	global_store_dwordx4 v[240:241], v[44:47], off
	v_lshl_add_u64 v[240:241], v[240:241], 0, s[100:101]
	ds_read_b128 v[246:249], v192 offset:14144
	s_waitcnt vmcnt(15) lgkmcnt(1)
	v_pk_fma_f32 v[50:51], v[244:245], v[210:211], v[50:51]
	v_pk_fma_f32 v[48:49], v[242:243], v[208:209], v[48:49]
	global_store_dwordx4 v[240:241], v[48:51], off
	v_lshl_add_u64 v[240:241], v[240:241], 0, s[100:101]
	ds_read_b128 v[242:245], v192 offset:15232
	s_waitcnt vmcnt(15) lgkmcnt(1)
	v_pk_fma_f32 v[54:55], v[248:249], v[210:211], v[54:55]
	v_pk_fma_f32 v[52:53], v[246:247], v[208:209], v[52:53]
	global_store_dwordx4 v[240:241], v[52:55], off
	v_lshl_add_u64 v[240:241], v[240:241], 0, s[100:101]
	ds_read_b128 v[246:249], v192 offset:16320
	s_waitcnt vmcnt(15) lgkmcnt(1)
	v_pk_fma_f32 v[58:59], v[244:245], v[210:211], v[58:59]
	v_pk_fma_f32 v[56:57], v[242:243], v[208:209], v[56:57]
	global_store_dwordx4 v[240:241], v[56:59], off
	v_lshl_add_u64 v[240:241], v[240:241], 0, s[100:101]
	s_waitcnt vmcnt(15) lgkmcnt(0)
	v_pk_fma_f32 v[62:63], v[248:249], v[210:211], v[62:63]
	v_pk_fma_f32 v[60:61], v[246:247], v[208:209], v[60:61]
	global_store_dwordx4 v[240:241], v[60:63], off
	v_lshl_add_u64 v[240:241], v[240:241], 0, s[100:101]
	s_and_b64 vcc, exec, s[2:3]
	s_barrier
	s_cbranch_vccnz .LBB0_776
